# attention steady loop: PV MFMAs 0-3 hoisted above rowmax (MFMA/VALU interleave), exps of first 4 gaps grouped after the rescale join
# speedup vs baseline: 1.0077x; 1.0077x over previous
.LBB0_264:
	s_waitcnt lgkmcnt(0)
	v_mfma_f32_32x32x16_bf16 v[144:159], v[220:223], v[184:187], v[80:95]
	v_add_f32_e32 v2, v112, v113
	v_add_f32_e32 v2, v114, v2
	v_add_f32_e32 v2, v115, v2
	s_lshl_b32 s2, s2, 1
	v_add_f32_e32 v2, v116, v2
	v_add_u32_e32 v0, s2, v233
	v_add_f32_e32 v2, v117, v2
	v_cvt_pk_bf16_f32 v188, v112, v113
	v_cvt_pk_bf16_f32 v189, v114, v115
	v_mfma_f32_32x32x16_bf16 v[128:143], v[216:219], v[184:187], v[80:95]
	v_add_f32_e32 v2, v118, v2
	v_add_f32_e32 v2, v119, v2
	v_add_f32_e32 v2, v120, v2
	v_add_f32_e32 v2, v121, v2
	v_cvt_pk_bf16_f32 v190, v116, v117
	v_cvt_pk_bf16_f32 v191, v118, v119
	v_mfma_f32_32x32x16_bf16 v[144:159], v[212:215], v[176:179], v[144:159]
	v_add_f32_e32 v2, v122, v2
	v_add_f32_e32 v2, v123, v2
	v_add_f32_e32 v2, v124, v2
	v_add_f32_e32 v2, v125, v2
	v_cvt_pk_bf16_f32 v180, v120, v121
	v_cvt_pk_bf16_f32 v181, v122, v123
	v_mfma_f32_32x32x16_bf16 v[128:143], v[208:211], v[176:179], v[128:143]
	v_add_f32_e32 v2, v126, v2
	v_add_f32_e32 v2, v127, v2
	v_add_f32_e32 v2, v96, v2
	v_add_f32_e32 v2, v97, v2
	v_cvt_pk_bf16_f32 v182, v124, v125
	v_cvt_pk_bf16_f32 v183, v126, v127
	v_mfma_f32_32x32x16_bf16 v[144:159], v[204:207], v[172:175], v[144:159]
	v_add_f32_e32 v2, v98, v2
	v_add_f32_e32 v2, v99, v2
	v_add_f32_e32 v2, v100, v2
	v_add_f32_e32 v2, v101, v2
	v_cvt_pk_bf16_f32 v168, v96, v97
	v_cvt_pk_bf16_f32 v169, v98, v99
	v_mfma_f32_32x32x16_bf16 v[128:143], v[200:203], v[172:175], v[128:143]
	v_add_f32_e32 v2, v102, v2
	v_add_f32_e32 v2, v103, v2
	v_add_f32_e32 v2, v104, v2
	v_add_f32_e32 v2, v105, v2
	v_cvt_pk_bf16_f32 v170, v100, v101
	v_cvt_pk_bf16_f32 v171, v102, v103
	v_mfma_f32_32x32x16_bf16 v[144:159], v[196:199], v[164:167], v[144:159]
	v_add_f32_e32 v2, v106, v2
	v_add_f32_e32 v2, v107, v2
	v_add_f32_e32 v2, v108, v2
	v_add_f32_e32 v2, v109, v2
	v_cvt_pk_bf16_f32 v160, v104, v105
	v_cvt_pk_bf16_f32 v161, v106, v107
	v_mfma_f32_32x32x16_bf16 v[128:143], v[192:195], v[164:167], v[128:143]
	v_add_f32_e32 v2, v110, v2
	v_add_f32_e32 v102, v111, v2
	v_cvt_pk_bf16_f32 v162, v108, v109
	v_cvt_pk_bf16_f32 v163, v110, v111
	ds_read_b64_tr_b16 v[96:97], v0 offset:24576
	ds_read_b64_tr_b16 v[98:99], v0 offset:25088
	ds_read_b64_tr_b16 v[10:11], v0 offset:28672
	ds_read_b64_tr_b16 v[12:13], v0 offset:29184
	ds_read_b64_tr_b16 v[6:7], v0 offset:32768
	ds_read_b64_tr_b16 v[8:9], v0 offset:33280
	ds_read_b64_tr_b16 v[2:3], v0 offset:36864
	ds_read_b64_tr_b16 v[4:5], v0 offset:37376
	v_lshl_add_u64 v[208:209], v[238:239], 0, s[54:55]
	v_lshl_add_u64 v[14:15], v[208:209], 0, s[74:75]
	s_add_i32 s2, s4, s22
	s_mov_b32 m0, s2
	s_nop 0
	global_load_lds_dwordx4 v[14:15], off
	v_lshl_add_u64 v[14:15], v[242:243], 0, s[54:55]
	v_lshl_add_u64 v[100:101], v[14:15], 0, s[66:67]
	s_lshl_b32 s2, s96, 1
	s_add_i32 s2, s2, s23
	s_mov_b32 m0, s2
	s_nop 0
	global_load_lds_dwordx4 v[100:101], off
	v_lshl_add_u64 v[100:101], v[14:15], 0, s[84:85]
	s_addk_i32 s2, 0x2000
	s_mov_b32 m0, s2
	s_nop 0
	global_load_lds_dwordx4 v[100:101], off
	v_add_f32_e32 v210, v235, v102
	s_waitcnt lgkmcnt(6)
	v_mfma_f32_32x32x16_bf16 v[64:79], v[188:191], v[96:99], v[64:79]
	ds_read_b64_tr_b16 v[100:101], v0 offset:25600
	ds_read_b64_tr_b16 v[102:103], v0 offset:26112
	v_max_f32_e32 v116, v144, v145
	v_max3_f32 v117, v146, v147, v129
	v_max3_f32 v116, v116, v128, v130
	v_max3_f32 v116, v116, v131, v148
	s_waitcnt lgkmcnt(6)
	v_mfma_f32_32x32x16_bf16 v[48:63], v[188:191], v[10:13], v[48:63]
	ds_read_b64_tr_b16 v[10:11], v0 offset:29696
	ds_read_b64_tr_b16 v[12:13], v0 offset:30208
	v_max3_f32 v117, v117, v150, v151
	v_max3_f32 v116, v116, v149, v132
	v_max3_f32 v117, v117, v134, v135
	v_max3_f32 v116, v116, v133, v152
	s_waitcnt lgkmcnt(6)
	v_mfma_f32_32x32x16_bf16 v[32:47], v[188:191], v[6:9], v[32:47]
	ds_read_b64_tr_b16 v[6:7], v0 offset:33792
	ds_read_b64_tr_b16 v[8:9], v0 offset:34304
	v_max3_f32 v117, v117, v154, v155
	v_max3_f32 v116, v116, v153, v136
	v_max3_f32 v117, v117, v138, v139
	v_max3_f32 v116, v116, v137, v156
	s_waitcnt lgkmcnt(6)
	v_mfma_f32_32x32x16_bf16 v[16:31], v[188:191], v[2:5], v[16:31]
	ds_read_b64_tr_b16 v[104:105], v0 offset:37888
	ds_read_b64_tr_b16 v[106:107], v0 offset:38400
	v_add_u32_e32 v2, s96, v232
	ds_read_b128 v[96:99], v2
	ds_read_b128 v[200:203], v2 offset:512
	v_max3_f32 v117, v117, v158, v159
	v_max3_f32 v116, v116, v157, v140
	v_max3_f32 v117, v117, v142, v143
	v_max3_f32 v116, v116, v141, v117
	v_mov_b32_e32 v117, v116
	s_nop 1
	v_permlane32_swap_b32_e32 v116, v117
	v_max_f32_e32 v116, v116, v117
	v_cmp_lt_f32_e32 vcc, s11, v116
	s_cmp_lg_u64 vcc, 0
	s_cselect_b64 s[46:47], -1, 0
	s_cbranch_vccnz .LBB0_272
.LBB0_265:
	v_exp_f32_e32 v144, v144
	v_exp_f32_e32 v145, v145
	v_exp_f32_e32 v146, v146
	v_exp_f32_e32 v147, v147
	v_exp_f32_e32 v148, v148
	v_exp_f32_e32 v149, v149
	v_exp_f32_e32 v150, v150
	v_exp_f32_e32 v151, v151
	s_waitcnt lgkmcnt(8)
	v_mfma_f32_32x32x16_bf16 v[64:79], v[180:183], v[100:103], v[64:79]
	v_exp_f32_e32 v152, v152
	v_exp_f32_e32 v153, v153
	ds_read_b64_tr_b16 v[100:101], v0 offset:26624
	ds_read_b64_tr_b16 v[102:103], v0 offset:27136
	ds_read_b128 v[204:207], v2 offset:2048
	ds_read_b128 v[196:199], v2 offset:2560
	s_waitcnt lgkmcnt(10)
	v_mfma_f32_32x32x16_bf16 v[48:63], v[180:183], v[10:13], v[48:63]
	v_exp_f32_e32 v154, v154
	v_exp_f32_e32 v155, v155
	ds_read_b64_tr_b16 v[108:109], v0 offset:30720
	ds_read_b64_tr_b16 v[110:111], v0 offset:31232
	ds_read_b128 v[192:195], v2 offset:4096
	ds_read_b128 v[10:13], v2 offset:4608
	s_waitcnt lgkmcnt(12)
	v_mfma_f32_32x32x16_bf16 v[32:47], v[180:183], v[6:9], v[32:47]
	v_exp_f32_e32 v156, v156
	v_exp_f32_e32 v157, v157
	ds_read_b64_tr_b16 v[112:113], v0 offset:34816
	ds_read_b64_tr_b16 v[114:115], v0 offset:35328
	ds_read_b128 v[6:9], v2 offset:6144
	ds_read_b128 v[2:5], v2 offset:6656
	s_waitcnt lgkmcnt(14)
	v_mfma_f32_32x32x16_bf16 v[16:31], v[180:183], v[104:107], v[16:31]
	v_exp_f32_e32 v158, v158
	v_exp_f32_e32 v159, v159
	ds_read_b64_tr_b16 v[104:105], v0 offset:38912
	ds_read_b64_tr_b16 v[106:107], v0 offset:39424
	s_waitcnt lgkmcnt(12)
	v_mfma_f32_32x32x16_bf16 v[64:79], v[168:171], v[100:103], v[64:79]
	v_exp_f32_e32 v128, v128
	v_exp_f32_e32 v129, v129
	ds_read_b64_tr_b16 v[100:101], v0 offset:27648
	ds_read_b64_tr_b16 v[102:103], v0 offset:28160
	s_waitcnt lgkmcnt(10)
	v_mfma_f32_32x32x16_bf16 v[48:63], v[168:171], v[108:111], v[48:63]
	v_exp_f32_e32 v130, v130
	v_exp_f32_e32 v131, v131
	ds_read_b64_tr_b16 v[108:109], v0 offset:31744
	ds_read_b64_tr_b16 v[110:111], v0 offset:32256
	s_waitcnt lgkmcnt(8)
	v_mfma_f32_32x32x16_bf16 v[32:47], v[168:171], v[112:115], v[32:47]
	v_exp_f32_e32 v132, v132
	v_exp_f32_e32 v133, v133
	ds_read_b64_tr_b16 v[112:113], v0 offset:35840
	ds_read_b64_tr_b16 v[114:115], v0 offset:36352
	s_waitcnt lgkmcnt(6)
	v_mfma_f32_32x32x16_bf16 v[16:31], v[168:171], v[104:107], v[16:31]
	v_exp_f32_e32 v134, v134
	v_exp_f32_e32 v135, v135
	ds_read_b64_tr_b16 v[104:105], v0 offset:39936
	ds_read_b64_tr_b16 v[106:107], v0 offset:40448
	s_waitcnt lgkmcnt(6)
	v_mfma_f32_32x32x16_bf16 v[64:79], v[160:163], v[100:103], v[64:79]
	v_exp_f32_e32 v136, v136
	v_exp_f32_e32 v137, v137
	s_waitcnt lgkmcnt(4)
	v_mfma_f32_32x32x16_bf16 v[48:63], v[160:163], v[108:111], v[48:63]
	v_exp_f32_e32 v138, v138
	v_exp_f32_e32 v139, v139
	s_waitcnt lgkmcnt(2)
	v_mfma_f32_32x32x16_bf16 v[32:47], v[160:163], v[112:115], v[32:47]
	v_exp_f32_e32 v140, v140
	v_exp_f32_e32 v141, v141
	s_waitcnt lgkmcnt(0)
	v_mfma_f32_32x32x16_bf16 v[16:31], v[160:163], v[104:107], v[16:31]
	v_exp_f32_e32 v142, v142
	v_exp_f32_e32 v143, v143
	s_waitcnt vmcnt(3) lgkmcnt(0)
	s_barrier
	s_andn2_b64 vcc, exec, s[46:47]
	v_add_u32_e32 v0, s88, v234
	s_cbranch_vccnz .LBB0_267
	s_waitcnt lgkmcnt(0)
	ds_read_b128 v[100:103], v0 offset:96
	ds_read_b128 v[104:107], v0 offset:64
	ds_read_b128 v[108:111], v0 offset:32
	ds_read_b128 v[112:115], v0
	s_waitcnt lgkmcnt(3)
	v_pk_mul_f32 v[76:77], v[76:77], v[100:101]
	s_waitcnt lgkmcnt(2)
	v_pk_mul_f32 v[72:73], v[72:73], v[104:105]
	s_waitcnt lgkmcnt(1)
	v_pk_mul_f32 v[68:69], v[68:69], v[108:109]
	v_pk_mul_f32 v[78:79], v[78:79], v[102:103]
	v_pk_mul_f32 v[74:75], v[74:75], v[106:107]
	v_pk_mul_f32 v[70:71], v[70:71], v[110:111]
	s_waitcnt lgkmcnt(0)
	v_pk_mul_f32 v[66:67], v[66:67], v[114:115]
	v_pk_mul_f32 v[64:65], v[64:65], v[112:113]
	v_pk_mul_f32 v[60:61], v[60:61], v[100:101]
	v_pk_mul_f32 v[56:57], v[56:57], v[104:105]
	v_pk_mul_f32 v[52:53], v[52:53], v[108:109]
	v_pk_mul_f32 v[62:63], v[62:63], v[102:103]
	v_pk_mul_f32 v[58:59], v[58:59], v[106:107]
	v_pk_mul_f32 v[54:55], v[54:55], v[110:111]
	v_pk_mul_f32 v[50:51], v[50:51], v[114:115]
	v_pk_mul_f32 v[48:49], v[48:49], v[112:113]
	v_pk_mul_f32 v[44:45], v[44:45], v[100:101]
	v_pk_mul_f32 v[40:41], v[40:41], v[104:105]
	v_pk_mul_f32 v[36:37], v[36:37], v[108:109]
	v_pk_mul_f32 v[46:47], v[46:47], v[102:103]
	v_pk_mul_f32 v[42:43], v[42:43], v[106:107]
	v_pk_mul_f32 v[38:39], v[38:39], v[110:111]
	v_pk_mul_f32 v[34:35], v[34:35], v[114:115]
	v_pk_mul_f32 v[32:33], v[32:33], v[112:113]
	v_pk_mul_f32 v[28:29], v[28:29], v[100:101]
	v_pk_mul_f32 v[24:25], v[24:25], v[104:105]
	v_pk_mul_f32 v[20:21], v[20:21], v[108:109]
	v_pk_mul_f32 v[30:31], v[30:31], v[102:103]
	v_pk_mul_f32 v[26:27], v[26:27], v[106:107]
	v_pk_mul_f32 v[22:23], v[22:23], v[110:111]
	v_pk_mul_f32 v[18:19], v[18:19], v[114:115]
	v_pk_mul_f32 v[16:17], v[16:17], v[112:113]
.LBB0_267:
	s_add_i32 s2, s96, 0x2000
	s_cmpk_lg_i32 s96, 0x4000
	s_cselect_b32 s24, s2, 0
	v_mfma_f32_32x32x16_bf16 v[112:127], v[96:99], v[184:187], v[80:95]
	v_add_f32_e32 v100, v144, v145
	v_add_f32_e32 v100, v146, v100
	v_add_f32_e32 v100, v147, v100
	s_lshl_b32 s2, s4, 1
	v_add_f32_e32 v100, v148, v100
	v_add_u32_e32 v229, s2, v233
	v_add_f32_e32 v96, v149, v100
	v_cvt_pk_bf16_f32 v188, v144, v145
	v_cvt_pk_bf16_f32 v189, v146, v147
	s_nop 0
	v_add_f32_e32 v96, v150, v96
	v_add_f32_e32 v96, v151, v96
	v_add_f32_e32 v96, v152, v96
	v_add_f32_e32 v144, v153, v96
	v_mfma_f32_32x32x16_bf16 v[96:111], v[200:203], v[184:187], v[80:95]
	v_cvt_pk_bf16_f32 v190, v148, v149
	v_cvt_pk_bf16_f32 v191, v150, v151
	v_mfma_f32_32x32x16_bf16 v[112:127], v[204:207], v[176:179], v[112:127]
	v_add_f32_e32 v144, v154, v144
	v_add_f32_e32 v144, v155, v144
	v_add_f32_e32 v144, v156, v144
	v_add_f32_e32 v144, v157, v144
	v_cvt_pk_bf16_f32 v180, v152, v153
	v_cvt_pk_bf16_f32 v181, v154, v155
	v_mfma_f32_32x32x16_bf16 v[96:111], v[196:199], v[176:179], v[96:111]
	v_add_f32_e32 v144, v158, v144
	v_add_f32_e32 v144, v159, v144
	v_add_f32_e32 v144, v128, v144
	v_add_f32_e32 v144, v129, v144
	v_cvt_pk_bf16_f32 v182, v156, v157
	v_cvt_pk_bf16_f32 v183, v158, v159
	v_mfma_f32_32x32x16_bf16 v[112:127], v[192:195], v[172:175], v[112:127]
	v_add_f32_e32 v144, v130, v144
	v_add_f32_e32 v144, v131, v144
	v_add_f32_e32 v144, v132, v144
	v_add_f32_e32 v144, v133, v144
	v_cvt_pk_bf16_f32 v168, v128, v129
	v_cvt_pk_bf16_f32 v169, v130, v131
	v_mfma_f32_32x32x16_bf16 v[96:111], v[10:13], v[172:175], v[96:111]
	v_add_f32_e32 v10, v134, v144
	v_add_f32_e32 v10, v135, v10
	v_add_f32_e32 v10, v136, v10
	v_add_f32_e32 v10, v137, v10
	v_cvt_pk_bf16_f32 v170, v132, v133
	v_cvt_pk_bf16_f32 v171, v134, v135
	v_mfma_f32_32x32x16_bf16 v[112:127], v[6:9], v[164:167], v[112:127]
	v_add_f32_e32 v6, v138, v10
	v_add_f32_e32 v6, v139, v6
	v_add_f32_e32 v6, v140, v6
	v_add_f32_e32 v6, v141, v6
	v_cvt_pk_bf16_f32 v160, v136, v137
	v_cvt_pk_bf16_f32 v161, v138, v139
	v_mfma_f32_32x32x16_bf16 v[96:111], v[2:5], v[164:167], v[96:111]
	v_add_f32_e32 v2, v142, v6
	v_add_f32_e32 v134, v143, v2
	v_cvt_pk_bf16_f32 v162, v140, v141
	v_cvt_pk_bf16_f32 v163, v142, v143
	ds_read_b64_tr_b16 v[128:129], v229 offset:24576
	ds_read_b64_tr_b16 v[130:131], v229 offset:25088
	ds_read_b64_tr_b16 v[10:11], v229 offset:28672
	ds_read_b64_tr_b16 v[12:13], v229 offset:29184
	ds_read_b64_tr_b16 v[6:7], v229 offset:32768
	ds_read_b64_tr_b16 v[8:9], v229 offset:33280
	ds_read_b64_tr_b16 v[2:3], v229 offset:36864
	ds_read_b64_tr_b16 v[4:5], v229 offset:37376
	s_mov_b64 s[2:3], 0xa0000
	v_lshl_add_u64 v[132:133], v[208:209], 0, s[2:3]
	s_add_i32 s2, s96, s22
	s_mov_b32 m0, s2
	s_nop 0
	global_load_lds_dwordx4 v[132:133], off
	s_mov_b64 s[2:3], 0xfe60000
	v_lshl_add_u64 v[132:133], v[14:15], 0, s[2:3]
	s_lshl_b32 s2, s24, 1
	s_add_i32 s4, s2, s23
	s_mov_b32 m0, s4
	s_nop 0
	global_load_lds_dwordx4 v[132:133], off
	s_mov_b64 s[2:3], 0xfe60080
	v_lshl_add_u64 v[14:15], v[14:15], 0, s[2:3]
	s_add_i32 s2, s4, 0x2000
	s_mov_b32 m0, s2
	s_nop 0
	global_load_lds_dwordx4 v[14:15], off
	v_add_f32_e32 v235, v210, v134
	s_waitcnt lgkmcnt(6)
	v_mfma_f32_32x32x16_bf16 v[64:79], v[188:191], v[128:131], v[64:79]
	ds_read_b64_tr_b16 v[128:129], v229 offset:25600
	ds_read_b64_tr_b16 v[130:131], v229 offset:26112
	v_max_f32_e32 v136, v112, v113
	v_max3_f32 v137, v114, v115, v97
	v_max3_f32 v136, v136, v96, v98
	v_max3_f32 v136, v136, v99, v116
	s_waitcnt lgkmcnt(6)
	v_mfma_f32_32x32x16_bf16 v[48:63], v[188:191], v[10:13], v[48:63]
	ds_read_b64_tr_b16 v[10:11], v229 offset:29696
	ds_read_b64_tr_b16 v[12:13], v229 offset:30208
	v_max3_f32 v137, v137, v118, v119
	v_max3_f32 v136, v136, v117, v100
	v_max3_f32 v137, v137, v102, v103
	v_max3_f32 v136, v136, v101, v120
	s_waitcnt lgkmcnt(6)
	v_mfma_f32_32x32x16_bf16 v[32:47], v[188:191], v[6:9], v[32:47]
	ds_read_b64_tr_b16 v[6:7], v229 offset:33792
	ds_read_b64_tr_b16 v[8:9], v229 offset:34304
	v_max3_f32 v137, v137, v122, v123
	v_max3_f32 v136, v136, v121, v104
	v_max3_f32 v137, v137, v106, v107
	v_max3_f32 v136, v136, v105, v124
	s_waitcnt lgkmcnt(6)
	v_mfma_f32_32x32x16_bf16 v[16:31], v[188:191], v[2:5], v[16:31]
	ds_read_b64_tr_b16 v[2:3], v229 offset:37888
	ds_read_b64_tr_b16 v[4:5], v229 offset:38400
	v_add_u32_e32 v14, s24, v232
	ds_read_b128 v[220:223], v14
	ds_read_b128 v[216:219], v14 offset:512
	v_max3_f32 v137, v137, v126, v127
	v_max3_f32 v136, v136, v125, v108
	v_max3_f32 v137, v137, v110, v111
	v_max3_f32 v136, v136, v109, v137
	v_mov_b32_e32 v137, v136
	s_nop 1
	v_permlane32_swap_b32_e32 v136, v137
	v_max_f32_e32 v136, v136, v137
	v_cmp_lt_f32_e32 vcc, s11, v136
	s_cmp_lg_u64 vcc, 0
	s_cselect_b64 s[46:47], -1, 0
	s_cbranch_vccnz .LBB0_275
.LBB0_268:
	v_exp_f32_e32 v112, v112
	v_exp_f32_e32 v113, v113
	v_exp_f32_e32 v114, v114
	v_exp_f32_e32 v115, v115
	v_exp_f32_e32 v116, v116
	v_exp_f32_e32 v117, v117
	v_exp_f32_e32 v118, v118
	v_exp_f32_e32 v119, v119
	s_waitcnt lgkmcnt(8)
	v_mfma_f32_32x32x16_bf16 v[64:79], v[180:183], v[128:131], v[64:79]
	v_exp_f32_e32 v120, v120
	v_exp_f32_e32 v121, v121
	ds_read_b64_tr_b16 v[128:129], v229 offset:26624
	ds_read_b64_tr_b16 v[130:131], v229 offset:27136
	ds_read_b128 v[212:215], v14 offset:2048
	ds_read_b128 v[208:211], v14 offset:2560
	s_waitcnt lgkmcnt(10)
	v_mfma_f32_32x32x16_bf16 v[48:63], v[180:183], v[10:13], v[48:63]
	v_exp_f32_e32 v122, v122
	v_exp_f32_e32 v123, v123
	ds_read_b64_tr_b16 v[10:11], v229 offset:30720
	ds_read_b64_tr_b16 v[12:13], v229 offset:31232
	ds_read_b128 v[204:207], v14 offset:4096
	ds_read_b128 v[200:203], v14 offset:4608
	s_waitcnt lgkmcnt(12)
	v_mfma_f32_32x32x16_bf16 v[32:47], v[180:183], v[6:9], v[32:47]
	v_exp_f32_e32 v124, v124
	v_exp_f32_e32 v125, v125
	ds_read_b64_tr_b16 v[6:7], v229 offset:34816
	ds_read_b64_tr_b16 v[8:9], v229 offset:35328
	ds_read_b128 v[196:199], v14 offset:6144
	ds_read_b128 v[192:195], v14 offset:6656
	s_waitcnt lgkmcnt(14)
	v_mfma_f32_32x32x16_bf16 v[16:31], v[180:183], v[2:5], v[16:31]
	v_exp_f32_e32 v126, v126
	v_exp_f32_e32 v127, v127
	ds_read_b64_tr_b16 v[2:3], v229 offset:38912
	ds_read_b64_tr_b16 v[4:5], v229 offset:39424
	s_waitcnt lgkmcnt(12)
	v_mfma_f32_32x32x16_bf16 v[64:79], v[168:171], v[128:131], v[64:79]
	v_exp_f32_e32 v96, v96
	v_exp_f32_e32 v97, v97
	ds_read_b64_tr_b16 v[128:129], v229 offset:27648
	ds_read_b64_tr_b16 v[130:131], v229 offset:28160
	s_waitcnt lgkmcnt(10)
	v_mfma_f32_32x32x16_bf16 v[48:63], v[168:171], v[10:13], v[48:63]
	v_exp_f32_e32 v98, v98
	v_exp_f32_e32 v99, v99
	ds_read_b64_tr_b16 v[10:11], v229 offset:31744
	ds_read_b64_tr_b16 v[12:13], v229 offset:32256
	s_waitcnt lgkmcnt(8)
	v_mfma_f32_32x32x16_bf16 v[32:47], v[168:171], v[6:9], v[32:47]
	v_exp_f32_e32 v100, v100
	v_exp_f32_e32 v101, v101
	ds_read_b64_tr_b16 v[6:7], v229 offset:35840
	ds_read_b64_tr_b16 v[8:9], v229 offset:36352
	s_waitcnt lgkmcnt(6)
	v_mfma_f32_32x32x16_bf16 v[16:31], v[168:171], v[2:5], v[16:31]
	v_exp_f32_e32 v102, v102
	v_exp_f32_e32 v103, v103
	ds_read_b64_tr_b16 v[2:3], v229 offset:39936
	ds_read_b64_tr_b16 v[4:5], v229 offset:40448
	s_waitcnt lgkmcnt(6)
	v_mfma_f32_32x32x16_bf16 v[64:79], v[160:163], v[128:131], v[64:79]
	v_exp_f32_e32 v104, v104
	v_exp_f32_e32 v105, v105
	s_waitcnt lgkmcnt(4)
	v_mfma_f32_32x32x16_bf16 v[48:63], v[160:163], v[10:13], v[48:63]
	v_exp_f32_e32 v106, v106
	v_exp_f32_e32 v107, v107
	s_waitcnt lgkmcnt(2)
	v_mfma_f32_32x32x16_bf16 v[32:47], v[160:163], v[6:9], v[32:47]
	v_exp_f32_e32 v108, v108
	v_exp_f32_e32 v109, v109
	s_waitcnt lgkmcnt(0)
	v_mfma_f32_32x32x16_bf16 v[16:31], v[160:163], v[2:5], v[16:31]
	v_exp_f32_e32 v110, v110
	v_exp_f32_e32 v111, v111
	s_waitcnt vmcnt(3) lgkmcnt(0)
	s_barrier
	s_andn2_b64 vcc, exec, s[46:47]
	s_cbranch_vccnz .LBB0_270
	s_waitcnt lgkmcnt(0)
	ds_read_b128 v[2:5], v0 offset:96
	ds_read_b128 v[6:9], v0 offset:64
	ds_read_b128 v[10:13], v0 offset:32
	ds_read_b128 v[128:131], v0
	s_waitcnt lgkmcnt(3)
	v_pk_mul_f32 v[76:77], v[76:77], v[2:3]
	s_waitcnt lgkmcnt(2)
	v_pk_mul_f32 v[72:73], v[72:73], v[6:7]
	s_waitcnt lgkmcnt(1)
	v_pk_mul_f32 v[68:69], v[68:69], v[10:11]
	v_pk_mul_f32 v[78:79], v[78:79], v[4:5]
	v_pk_mul_f32 v[74:75], v[74:75], v[8:9]
	v_pk_mul_f32 v[70:71], v[70:71], v[12:13]
	s_waitcnt lgkmcnt(0)
	v_pk_mul_f32 v[66:67], v[66:67], v[130:131]
	v_pk_mul_f32 v[64:65], v[64:65], v[128:129]
	v_pk_mul_f32 v[60:61], v[60:61], v[2:3]
	v_pk_mul_f32 v[56:57], v[56:57], v[6:7]
	v_pk_mul_f32 v[52:53], v[52:53], v[10:11]
	v_pk_mul_f32 v[62:63], v[62:63], v[4:5]
	v_pk_mul_f32 v[58:59], v[58:59], v[8:9]
	v_pk_mul_f32 v[54:55], v[54:55], v[12:13]
	v_pk_mul_f32 v[50:51], v[50:51], v[130:131]
	v_pk_mul_f32 v[48:49], v[48:49], v[128:129]
	v_pk_mul_f32 v[44:45], v[44:45], v[2:3]
	v_pk_mul_f32 v[40:41], v[40:41], v[6:7]
	v_pk_mul_f32 v[36:37], v[36:37], v[10:11]
	v_pk_mul_f32 v[46:47], v[46:47], v[4:5]
	v_pk_mul_f32 v[42:43], v[42:43], v[8:9]
	v_pk_mul_f32 v[38:39], v[38:39], v[12:13]
	v_pk_mul_f32 v[34:35], v[34:35], v[130:131]
	v_pk_mul_f32 v[32:33], v[32:33], v[128:129]
	v_pk_mul_f32 v[28:29], v[28:29], v[2:3]
	v_pk_mul_f32 v[24:25], v[24:25], v[6:7]
	v_pk_mul_f32 v[20:21], v[20:21], v[10:11]
	v_pk_mul_f32 v[30:31], v[30:31], v[4:5]
	v_pk_mul_f32 v[26:27], v[26:27], v[8:9]
	v_pk_mul_f32 v[22:23], v[22:23], v[12:13]
	v_pk_mul_f32 v[18:19], v[18:19], v[130:131]
	v_pk_mul_f32 v[16:17], v[16:17], v[128:129]

.LBB0_272:
	v_max_f32_e32 v80, v116, v116
	v_max_f32_e32 v116, 0, v80
	v_exp_f32_e64 v117, -v116
	v_add_f32_e32 v227, v227, v116
	v_xor_b32_e32 v80, 0x80000000, v227
	v_mov_b32_e32 v81, v80
	v_mov_b32_e32 v82, v80
	v_mov_b32_e32 v83, v80
	v_mov_b32_e32 v84, v80
	v_mov_b32_e32 v85, v80
	v_mov_b32_e32 v86, v80
	v_mov_b32_e32 v87, v80
	v_mov_b32_e32 v88, v80
	v_mov_b32_e32 v89, v80
	v_mov_b32_e32 v90, v80
	v_mov_b32_e32 v91, v80
	v_mov_b32_e32 v92, v80
	v_mov_b32_e32 v93, v80
	v_mov_b32_e32 v94, v80
	v_mov_b32_e32 v95, v80
	s_and_saveexec_b64 s[48:49], s[38:39]
	ds_write_b32 v224, v117
	s_or_b64 exec, exec, s[48:49]
	v_sub_f32_e32 v159, v159, v116
	v_sub_f32_e32 v158, v158, v116
	v_sub_f32_e32 v157, v157, v116
	v_sub_f32_e32 v156, v156, v116
	v_sub_f32_e32 v155, v155, v116
	v_sub_f32_e32 v154, v154, v116
	v_sub_f32_e32 v153, v153, v116
	v_sub_f32_e32 v152, v152, v116
	v_sub_f32_e32 v151, v151, v116
	v_sub_f32_e32 v150, v150, v116
	v_sub_f32_e32 v149, v149, v116
	v_sub_f32_e32 v148, v148, v116
	v_sub_f32_e32 v147, v147, v116
	v_sub_f32_e32 v146, v146, v116
	v_sub_f32_e32 v145, v145, v116
	v_sub_f32_e32 v144, v144, v116
	v_sub_f32_e32 v143, v143, v116
	v_sub_f32_e32 v142, v142, v116
	v_sub_f32_e32 v141, v141, v116
	v_sub_f32_e32 v140, v140, v116
	v_sub_f32_e32 v139, v139, v116
	v_sub_f32_e32 v138, v138, v116
	v_sub_f32_e32 v137, v137, v116
	v_sub_f32_e32 v136, v136, v116
	v_sub_f32_e32 v135, v135, v116
	v_sub_f32_e32 v134, v134, v116
	v_sub_f32_e32 v133, v133, v116
	v_sub_f32_e32 v132, v132, v116
	v_sub_f32_e32 v131, v131, v116
	v_sub_f32_e32 v130, v130, v116
	v_sub_f32_e32 v129, v129, v116
	v_sub_f32_e32 v128, v128, v116
	v_mul_f32_e32 v210, v210, v117
	s_branch .LBB0_265
.LBB0_275:
	v_max_f32_e32 v136, v136, v136
	v_max_f32_e32 v136, 0, v136
	v_exp_f32_e64 v137, -v136
	v_add_f32_e32 v227, v227, v136
	v_xor_b32_e32 v80, 0x80000000, v227
	v_mov_b32_e32 v81, v80
	v_mov_b32_e32 v82, v80
	v_mov_b32_e32 v83, v80
	v_mov_b32_e32 v84, v80
	v_mov_b32_e32 v85, v80
	v_mov_b32_e32 v86, v80
	v_mov_b32_e32 v87, v80
	v_mov_b32_e32 v88, v80
	v_mov_b32_e32 v89, v80
	v_mov_b32_e32 v90, v80
	v_mov_b32_e32 v91, v80
	v_mov_b32_e32 v92, v80
	v_mov_b32_e32 v93, v80
	v_mov_b32_e32 v94, v80
	v_mov_b32_e32 v95, v80
	s_and_saveexec_b64 s[48:49], s[38:39]
	ds_write_b32 v224, v137
	s_or_b64 exec, exec, s[48:49]
	v_sub_f32_e32 v127, v127, v136
	v_sub_f32_e32 v126, v126, v136
	v_sub_f32_e32 v125, v125, v136
	v_sub_f32_e32 v124, v124, v136
	v_sub_f32_e32 v123, v123, v136
	v_sub_f32_e32 v122, v122, v136
	v_sub_f32_e32 v121, v121, v136
	v_sub_f32_e32 v120, v120, v136
	v_sub_f32_e32 v119, v119, v136
	v_sub_f32_e32 v118, v118, v136
	v_sub_f32_e32 v117, v117, v136
	v_sub_f32_e32 v116, v116, v136
	v_sub_f32_e32 v115, v115, v136
	v_sub_f32_e32 v114, v114, v136
	v_sub_f32_e32 v113, v113, v136
	v_sub_f32_e32 v112, v112, v136
	v_sub_f32_e32 v111, v111, v136
	v_sub_f32_e32 v110, v110, v136
	v_sub_f32_e32 v109, v109, v136
	v_sub_f32_e32 v108, v108, v136
	v_sub_f32_e32 v107, v107, v136
	v_sub_f32_e32 v106, v106, v136
	v_sub_f32_e32 v105, v105, v136
	v_sub_f32_e32 v104, v104, v136
	v_sub_f32_e32 v103, v103, v136
	v_sub_f32_e32 v102, v102, v136
	v_sub_f32_e32 v101, v101, v136
	v_sub_f32_e32 v100, v100, v136
	v_sub_f32_e32 v99, v99, v136
	v_sub_f32_e32 v98, v98, v136
	v_sub_f32_e32 v97, v97, v136
	v_sub_f32_e32 v96, v96, v136
	v_mul_f32_e32 v235, v235, v137
	s_branch .LBB0_268
